# per-XCD attention queues: an empty own queue is followed by one 8-lane read of all counters (instead of trying the other seven queues one by one), exp2 wrapper removal kept
# baseline (speedup 1.0000x reference)
.LBB0_797:
.Lq_again:
	s_lshl_b32 s12, s100, 7
	s_add_i32 s12, s12, 0x8000
	v_mov_b32_e32 v0, s12
	v_mov_b32_e32 v1, 1
	s_and_saveexec_b64 s[12:13], s[10:11]
	global_atomic_add v1, v0, v1, s[38:39] sc0
	s_or_b64 exec, exec, s[12:13]
	s_waitcnt vmcnt(0)
	v_readfirstlane_b32 s43, v1
	s_cmpk_lt_u32 s43, 0x800
	s_cbranch_scc1 .Lq_got
	v_mbcnt_lo_u32_b32 v0, -1, 0
	v_mbcnt_hi_u32_b32 v0, -1, v0
	v_lshlrev_b32_e32 v0, 7, v0
	v_add_u32_e32 v0, 0x8000, v0
	v_mov_b32_e32 v1, 0
	s_mov_b64 exec, 0xff
	global_atomic_add v1, v0, v1, s[38:39] sc0
	s_mov_b64 exec, -1
	s_waitcnt vmcnt(0)
	v_cmp_gt_u32_e32 vcc, 0x800, v1
	s_nop 1
	s_and_b32 s12, vcc_lo, 0xff
	s_cbranch_scc0 .Lq_done
	s_ff1_i32_b32 s100, s12
	s_branch .Lq_again
.Lq_done:
	s_mov_b64 s[12:13], -1
	s_branch .LBB0_796
